# v77 + th0 + gfma (gates: 255*sigmoid = rcp(e*c+c), one fma+rcp, no final multiply) + sw2 (both split-barrier words fetched in the first wait before thin stage 0)
# baseline (speedup 1.0000x reference)
.LBB0_394:
	v_mul_f32_e32 v146, 0xbfb8aa3b, v122
	v_mul_f32_e32 v147, 0xbfb8aa3b, v118
	v_mul_f32_e32 v148, 0xbfb8aa3b, v123
	v_mul_f32_e32 v149, 0xbfb8aa3b, v119
	v_mul_f32_e32 v150, 0xbfb8aa3b, v124
	v_mul_f32_e32 v151, 0xbfb8aa3b, v120
	v_mul_f32_e32 v155, 0xbfb8aa3b, v125
	v_mul_f32_e32 v156, 0xbfb8aa3b, v121
	v_mul_f32_e32 v157, 0xbfb8aa3b, v102
	v_mul_f32_e32 v158, 0xbfb8aa3b, v98
	v_mul_f32_e32 v159, 0xbfb8aa3b, v103
	v_mul_f32_e32 v160, 0xbfb8aa3b, v99
	v_mul_f32_e32 v161, 0xbfb8aa3b, v104
	v_mul_f32_e32 v170, 0xbfb8aa3b, v100
	v_mul_f32_e32 v185, 0xbfb8aa3b, v105
	v_mul_f32_e32 v186, 0xbfb8aa3b, v101
	v_mul_f32_e32 v187, 0xbfb8aa3b, v86
	v_mul_f32_e32 v188, 0xbfb8aa3b, v82
	v_mul_f32_e32 v189, 0xbfb8aa3b, v87
	v_mul_f32_e32 v191, 0xbfb8aa3b, v83
	v_mul_f32_e32 v205, 0xbfb8aa3b, v88
	v_mul_f32_e32 v206, 0xbfb8aa3b, v84
	v_mul_f32_e32 v219, 0xbfb8aa3b, v89
	v_mul_f32_e32 v220, 0xbfb8aa3b, v85
	v_mul_f32_e32 v221, 0xbfb8aa3b, v70
	v_mul_f32_e32 v222, 0xbfb8aa3b, v66
	v_mul_f32_e32 v223, 0xbfb8aa3b, v71
	v_mul_f32_e32 v224, 0xbfb8aa3b, v67
	v_mul_f32_e32 v225, 0xbfb8aa3b, v72
	v_mul_f32_e32 v226, 0xbfb8aa3b, v68
	v_mul_f32_e32 v227, 0xbfb8aa3b, v73
	v_mul_f32_e32 v228, 0xbfb8aa3b, v69
	v_exp_f32_e32 v217, v146
	v_exp_f32_e32 v152, v147
	v_exp_f32_e32 v218, v148
	v_exp_f32_e32 v153, v149
	v_exp_f32_e32 v154, v150
	v_exp_f32_e32 v150, v151
	v_exp_f32_e32 v155, v155
	v_exp_f32_e32 v151, v156
	v_exp_f32_e32 v215, v157
	v_exp_f32_e32 v211, v158
	v_exp_f32_e32 v216, v159
	v_exp_f32_e32 v212, v160
	v_exp_f32_e32 v213, v161
	v_exp_f32_e32 v209, v170
	v_exp_f32_e32 v214, v185
	v_exp_f32_e32 v210, v186
	v_exp_f32_e32 v207, v187
	v_exp_f32_e32 v190, v188
	v_exp_f32_e32 v208, v189
	v_exp_f32_e32 v191, v191
	v_exp_f32_e32 v205, v205
	v_exp_f32_e32 v156, v206
	v_exp_f32_e32 v206, v219
	v_exp_f32_e32 v157, v220
	v_exp_f32_e32 v188, v221
	v_exp_f32_e32 v160, v222
	v_exp_f32_e32 v189, v223
	v_exp_f32_e32 v161, v224
	v_exp_f32_e32 v186, v225
	v_exp_f32_e32 v158, v226
	v_exp_f32_e32 v187, v227
	v_exp_f32_e32 v159, v228
	s_cmp_gt_u32 s72, 16
	v_ashrrev_i32_e32 v185, 31, v184
	s_cbranch_scc0 .LBB0_414
	v_mov_b32_e32 v247, 0x3b808081
	s_sub_i32 s2, s72, 17
	s_cmp_lt_u32 s2, 4
	s_mov_b32 s0, 0xb600000
	s_cselect_b32 s0, s0, 0xb600400
	v_readlane_b32 s6, v246, 2
	v_readlane_b32 s7, v246, 3
	s_add_u32 s0, s6, s0
	s_addc_u32 s1, s7, 0
	s_lshl_b32 s2, s2, 8
	s_and_b32 s2, s2, 0x300
	v_or_b32_e32 v170, s2, v175
	v_lshl_add_u64 v[148:149], s[0:1], 0, v[170:171]
	v_mul_f32_e32 v170, 0xbfb8aa3b, v130
	v_exp_f32_e32 v170, v170
	v_mul_f32_e32 v220, 0xbfb8aa3b, v131
	v_exp_f32_e32 v220, v220
	v_mul_f32_e32 v222, 0xbfb8aa3b, v132
	v_exp_f32_e32 v222, v222
	v_fmamk_f32 v170, v170, 0x3b808081, v247
	v_mul_f32_e32 v224, 0xbfb8aa3b, v133
	v_rcp_f32_e32 v170, v170
	v_fmamk_f32 v220, v220, 0x3b808081, v247
	v_exp_f32_e32 v224, v224
	v_mul_f32_e32 v219, 0xbfb8aa3b, v126
	v_rcp_f32_e32 v220, v220
	v_exp_f32_e32 v219, v219
	v_mul_f32_e32 v221, 0xbfb8aa3b, v127
	v_fmamk_f32 v222, v222, 0x3b808081, v247
	v_exp_f32_e32 v221, v221
	v_rcp_f32_e32 v222, v222
	v_mul_f32_e32 v223, 0xbfb8aa3b, v128
	v_fmamk_f32 v224, v224, 0x3b808081, v247
	v_exp_f32_e32 v223, v223
	v_rcp_f32_e32 v224, v224
	v_fmamk_f32 v219, v219, 0x3b808081, v247
	v_mul_f32_e32 v225, 0xbfb8aa3b, v129
	v_cvt_pk_u8_f32 v170, v170, 0, 0
	v_rcp_f32_e32 v219, v219
	v_fmamk_f32 v221, v221, 0x3b808081, v247
	v_exp_f32_e32 v225, v225
	v_cvt_pk_u8_f32 v170, v220, 1, v170
	v_rcp_f32_e32 v221, v221
	v_fmamk_f32 v223, v223, 0x3b808081, v247
	v_cvt_pk_u8_f32 v170, v222, 2, v170
	v_rcp_f32_e32 v223, v223
	v_fmamk_f32 v225, v225, 0x3b808081, v247
	v_cvt_pk_u8_f32 v220, v224, 3, v170
	v_mov_b32_e32 v170, v219
	v_rcp_f32_e32 v225, v225
	v_cvt_pk_u8_f32 v170, v170, 0, 0
	v_cvt_pk_u8_f32 v170, v221, 1, v170
	v_cvt_pk_u8_f32 v170, v223, 2, v170
	v_lshlrev_b64 v[146:147], 11, v[184:185]
	v_lshl_add_u64 v[146:147], v[148:149], 0, v[146:147]
	v_cvt_pk_u8_f32 v221, v225, 3, v170
	v_fmamk_f32 v170, v217, 0x3b808081, v247
	global_store_dwordx2 v[146:147], v[220:221], off nt
	v_rcp_f32_e32 v170, v170
	v_fmamk_f32 v220, v218, 0x3b808081, v247
	v_rcp_f32_e32 v220, v220
	v_fmamk_f32 v222, v154, 0x3b808081, v247
	v_rcp_f32_e32 v222, v222
	v_fmamk_f32 v224, v155, 0x3b808081, v247
	v_rcp_f32_e32 v224, v224
	v_fmamk_f32 v219, v152, 0x3b808081, v247
	v_cvt_pk_u8_f32 v170, v170, 0, 0
	v_rcp_f32_e32 v219, v219
	v_fmamk_f32 v221, v153, 0x3b808081, v247
	v_cvt_pk_u8_f32 v170, v220, 1, v170
	v_rcp_f32_e32 v221, v221
	v_fmamk_f32 v223, v150, 0x3b808081, v247
	v_cvt_pk_u8_f32 v170, v222, 2, v170
	v_rcp_f32_e32 v223, v223
	v_fmamk_f32 v225, v151, 0x3b808081, v247
	v_cvt_pk_u8_f32 v220, v224, 3, v170
	v_mov_b32_e32 v170, v219
	v_rcp_f32_e32 v225, v225
	v_cvt_pk_u8_f32 v170, v170, 0, 0
	v_cvt_pk_u8_f32 v170, v221, 1, v170
	v_cvt_pk_u8_f32 v170, v223, 2, v170
	v_cvt_pk_u8_f32 v221, v225, 3, v170
	v_mul_f32_e32 v170, 0xbfb8aa3b, v110
	v_exp_f32_e32 v170, v170
	v_mul_f32_e32 v222, 0xbfb8aa3b, v111
	v_exp_f32_e32 v222, v222
	v_mul_f32_e32 v224, 0xbfb8aa3b, v112
	v_exp_f32_e32 v224, v224
	v_fmamk_f32 v170, v170, 0x3b808081, v247
	v_mul_f32_e32 v226, 0xbfb8aa3b, v113
	v_rcp_f32_e32 v170, v170
	v_fmamk_f32 v222, v222, 0x3b808081, v247
	v_exp_f32_e32 v226, v226
	v_mul_f32_e32 v219, 0xbfb8aa3b, v106
	v_rcp_f32_e32 v222, v222
	v_exp_f32_e32 v219, v219
	v_mul_f32_e32 v223, 0xbfb8aa3b, v107
	v_fmamk_f32 v224, v224, 0x3b808081, v247
	v_exp_f32_e32 v223, v223
	v_rcp_f32_e32 v224, v224
	v_mul_f32_e32 v225, 0xbfb8aa3b, v108
	v_fmamk_f32 v226, v226, 0x3b808081, v247
	v_exp_f32_e32 v225, v225
	v_rcp_f32_e32 v226, v226
	v_fmamk_f32 v219, v219, 0x3b808081, v247
	v_mul_f32_e32 v227, 0xbfb8aa3b, v109
	v_cvt_pk_u8_f32 v170, v170, 0, 0
	v_rcp_f32_e32 v219, v219
	v_fmamk_f32 v223, v223, 0x3b808081, v247
	v_exp_f32_e32 v227, v227
	v_cvt_pk_u8_f32 v170, v222, 1, v170
	v_rcp_f32_e32 v223, v223
	v_fmamk_f32 v225, v225, 0x3b808081, v247
	v_cvt_pk_u8_f32 v170, v224, 2, v170
	v_rcp_f32_e32 v225, v225
	v_fmamk_f32 v227, v227, 0x3b808081, v247
	v_cvt_pk_u8_f32 v222, v226, 3, v170
	v_mov_b32_e32 v170, v219
	v_rcp_f32_e32 v227, v227
	v_cvt_pk_u8_f32 v170, v170, 0, 0
	v_cvt_pk_u8_f32 v170, v223, 1, v170
	global_store_dwordx2 v[146:147], v[220:221], off offset:128 nt
	v_or_b32_e32 v220, 16, v184
	v_ashrrev_i32_e32 v221, 31, v220
	v_cvt_pk_u8_f32 v170, v225, 2, v170
	v_lshlrev_b64 v[220:221], 11, v[220:221]
	v_lshl_add_u64 v[220:221], v[148:149], 0, v[220:221]
	v_cvt_pk_u8_f32 v223, v227, 3, v170
	v_fmamk_f32 v170, v215, 0x3b808081, v247
	global_store_dwordx2 v[220:221], v[222:223], off nt
	v_rcp_f32_e32 v170, v170
	v_fmamk_f32 v222, v216, 0x3b808081, v247
	v_rcp_f32_e32 v222, v222
	v_fmamk_f32 v224, v213, 0x3b808081, v247
	v_rcp_f32_e32 v224, v224
	v_fmamk_f32 v226, v214, 0x3b808081, v247
	v_rcp_f32_e32 v226, v226
	v_fmamk_f32 v219, v211, 0x3b808081, v247
	v_cvt_pk_u8_f32 v170, v170, 0, 0
	v_rcp_f32_e32 v219, v219
	v_fmamk_f32 v223, v212, 0x3b808081, v247
	v_cvt_pk_u8_f32 v170, v222, 1, v170
	v_rcp_f32_e32 v223, v223
	v_fmamk_f32 v225, v209, 0x3b808081, v247
	v_cvt_pk_u8_f32 v170, v224, 2, v170
	v_rcp_f32_e32 v225, v225
	v_fmamk_f32 v227, v210, 0x3b808081, v247
	v_cvt_pk_u8_f32 v222, v226, 3, v170
	v_mov_b32_e32 v170, v219
	v_rcp_f32_e32 v227, v227
	v_cvt_pk_u8_f32 v170, v170, 0, 0
	v_cvt_pk_u8_f32 v170, v223, 1, v170
	v_cvt_pk_u8_f32 v170, v225, 2, v170
	v_cvt_pk_u8_f32 v223, v227, 3, v170
	v_mul_f32_e32 v170, 0xbfb8aa3b, v94
	global_store_dwordx2 v[220:221], v[222:223], off offset:128 nt
	v_exp_f32_e32 v170, v170
	v_mul_f32_e32 v222, 0xbfb8aa3b, v95
	v_exp_f32_e32 v222, v222
	v_mul_f32_e32 v224, 0xbfb8aa3b, v96
	v_exp_f32_e32 v224, v224
	v_fmamk_f32 v170, v170, 0x3b808081, v247
	v_mul_f32_e32 v226, 0xbfb8aa3b, v97
	v_rcp_f32_e32 v170, v170
	v_fmamk_f32 v222, v222, 0x3b808081, v247
	v_exp_f32_e32 v226, v226
	v_mul_f32_e32 v219, 0xbfb8aa3b, v90
	v_rcp_f32_e32 v222, v222
	v_exp_f32_e32 v219, v219
	v_mul_f32_e32 v223, 0xbfb8aa3b, v91
	v_fmamk_f32 v224, v224, 0x3b808081, v247
	v_exp_f32_e32 v223, v223
	v_rcp_f32_e32 v224, v224
	v_mul_f32_e32 v225, 0xbfb8aa3b, v92
	v_fmamk_f32 v226, v226, 0x3b808081, v247
	v_exp_f32_e32 v225, v225
	v_rcp_f32_e32 v226, v226
	v_fmamk_f32 v219, v219, 0x3b808081, v247
	v_mul_f32_e32 v227, 0xbfb8aa3b, v93
	v_cvt_pk_u8_f32 v170, v170, 0, 0
	v_rcp_f32_e32 v219, v219
	v_fmamk_f32 v223, v223, 0x3b808081, v247
	v_exp_f32_e32 v227, v227
	v_cvt_pk_u8_f32 v170, v222, 1, v170
	v_rcp_f32_e32 v223, v223
	v_fmamk_f32 v225, v225, 0x3b808081, v247
	v_cvt_pk_u8_f32 v170, v224, 2, v170
	v_rcp_f32_e32 v225, v225
	v_fmamk_f32 v227, v227, 0x3b808081, v247
	v_cvt_pk_u8_f32 v222, v226, 3, v170
	v_mov_b32_e32 v170, v219
	v_rcp_f32_e32 v227, v227
	v_cvt_pk_u8_f32 v170, v170, 0, 0
	v_cvt_pk_u8_f32 v170, v223, 1, v170
	v_or_b32_e32 v220, 32, v184
	v_ashrrev_i32_e32 v221, 31, v220
	v_cvt_pk_u8_f32 v170, v225, 2, v170
	v_lshlrev_b64 v[220:221], 11, v[220:221]
	v_lshl_add_u64 v[220:221], v[148:149], 0, v[220:221]
	v_cvt_pk_u8_f32 v223, v227, 3, v170
	v_fmamk_f32 v170, v207, 0x3b808081, v247
	global_store_dwordx2 v[220:221], v[222:223], off nt
	v_rcp_f32_e32 v170, v170
	v_fmamk_f32 v222, v208, 0x3b808081, v247
	v_rcp_f32_e32 v222, v222
	v_fmamk_f32 v224, v205, 0x3b808081, v247
	v_rcp_f32_e32 v224, v224
	v_fmamk_f32 v226, v206, 0x3b808081, v247
	v_rcp_f32_e32 v226, v226
	v_fmamk_f32 v219, v190, 0x3b808081, v247
	v_cvt_pk_u8_f32 v170, v170, 0, 0
	v_rcp_f32_e32 v219, v219
	v_fmamk_f32 v223, v191, 0x3b808081, v247
	v_cvt_pk_u8_f32 v170, v222, 1, v170
	v_rcp_f32_e32 v223, v223
	v_fmamk_f32 v225, v156, 0x3b808081, v247
	v_cvt_pk_u8_f32 v170, v224, 2, v170
	v_rcp_f32_e32 v225, v225
	v_fmamk_f32 v227, v157, 0x3b808081, v247
	v_cvt_pk_u8_f32 v222, v226, 3, v170
	v_mov_b32_e32 v170, v219
	v_rcp_f32_e32 v227, v227
	v_cvt_pk_u8_f32 v170, v170, 0, 0
	v_cvt_pk_u8_f32 v170, v223, 1, v170
	v_cvt_pk_u8_f32 v170, v225, 2, v170
	v_cvt_pk_u8_f32 v223, v227, 3, v170
	global_store_dwordx2 v[220:221], v[222:223], off offset:128 nt
	v_or_b32_e32 v220, 48, v184
	v_ashrrev_i32_e32 v221, 31, v220
	v_lshlrev_b64 v[220:221], 11, v[220:221]
	v_mul_f32_e32 v170, 0xbfb8aa3b, v78
	v_exp_f32_e32 v170, v170
	v_lshl_add_u64 v[148:149], v[148:149], 0, v[220:221]
	v_mul_f32_e32 v220, 0xbfb8aa3b, v79
	v_exp_f32_e32 v220, v220
	v_mul_f32_e32 v222, 0xbfb8aa3b, v80
	v_exp_f32_e32 v222, v222
	v_fmamk_f32 v170, v170, 0x3b808081, v247
	v_mul_f32_e32 v224, 0xbfb8aa3b, v81
	v_rcp_f32_e32 v170, v170
	v_fmamk_f32 v220, v220, 0x3b808081, v247
	v_exp_f32_e32 v224, v224
	v_mul_f32_e32 v219, 0xbfb8aa3b, v74
	v_rcp_f32_e32 v220, v220
	v_exp_f32_e32 v219, v219
	v_mul_f32_e32 v221, 0xbfb8aa3b, v75
	v_fmamk_f32 v222, v222, 0x3b808081, v247
	v_exp_f32_e32 v221, v221
	v_rcp_f32_e32 v222, v222
	v_mul_f32_e32 v223, 0xbfb8aa3b, v76
	v_fmamk_f32 v224, v224, 0x3b808081, v247
	v_exp_f32_e32 v223, v223
	v_rcp_f32_e32 v224, v224
	v_fmamk_f32 v219, v219, 0x3b808081, v247
	v_mul_f32_e32 v225, 0xbfb8aa3b, v77
	v_cvt_pk_u8_f32 v170, v170, 0, 0
	v_rcp_f32_e32 v219, v219
	v_fmamk_f32 v221, v221, 0x3b808081, v247
	v_exp_f32_e32 v225, v225
	v_cvt_pk_u8_f32 v170, v220, 1, v170
	v_rcp_f32_e32 v221, v221
	v_fmamk_f32 v223, v223, 0x3b808081, v247
	v_cvt_pk_u8_f32 v170, v222, 2, v170
	v_rcp_f32_e32 v223, v223
	v_fmamk_f32 v225, v225, 0x3b808081, v247
	v_cvt_pk_u8_f32 v220, v224, 3, v170
	v_mov_b32_e32 v170, v219
	v_rcp_f32_e32 v225, v225
	v_cvt_pk_u8_f32 v170, v170, 0, 0
	v_cvt_pk_u8_f32 v170, v221, 1, v170
	v_cvt_pk_u8_f32 v170, v223, 2, v170
	v_cvt_pk_u8_f32 v221, v225, 3, v170
	v_fmamk_f32 v170, v188, 0x3b808081, v247
	global_store_dwordx2 v[148:149], v[220:221], off nt
	v_rcp_f32_e32 v170, v170
	v_fmamk_f32 v220, v189, 0x3b808081, v247
	v_rcp_f32_e32 v220, v220
	v_fmamk_f32 v222, v186, 0x3b808081, v247
	v_rcp_f32_e32 v222, v222
	v_fmamk_f32 v224, v187, 0x3b808081, v247
	v_rcp_f32_e32 v224, v224
	v_fmamk_f32 v219, v160, 0x3b808081, v247
	v_cvt_pk_u8_f32 v170, v170, 0, 0
	v_rcp_f32_e32 v219, v219
	v_fmamk_f32 v221, v161, 0x3b808081, v247
	v_cvt_pk_u8_f32 v170, v220, 1, v170
	v_rcp_f32_e32 v221, v221
	v_fmamk_f32 v223, v158, 0x3b808081, v247
	v_cvt_pk_u8_f32 v170, v222, 2, v170
	v_rcp_f32_e32 v223, v223
	v_fmamk_f32 v225, v159, 0x3b808081, v247
	v_cvt_pk_u8_f32 v220, v224, 3, v170
	v_mov_b32_e32 v170, v219
	v_rcp_f32_e32 v225, v225
	v_cvt_pk_u8_f32 v170, v170, 0, 0
	v_cvt_pk_u8_f32 v170, v221, 1, v170
	v_cvt_pk_u8_f32 v170, v223, 2, v170
	v_cvt_pk_u8_f32 v221, v225, 3, v170
	s_cmpk_gt_i32 s53, 0x154f
	global_store_dwordx2 v[148:149], v[220:221], off offset:128 nt
	s_cbranch_scc1 .LBB0_413
	s_waitcnt vmcnt(8)
	global_store_dwordx4 v[248:249], v[114:117], off nt
	global_store_dwordx4 v[250:251], v[134:137], off nt
	global_store_dwordx4 v[252:253], v[138:141], off nt
	global_store_dwordx4 v[254:255], v[142:145], off nt
.LBB0_413:
	v_mul_f32_e32 v148, 0xbfb8aa3b, v62
	v_exp_f32_e32 v170, v148
	v_mul_f32_e32 v220, 0xbfb8aa3b, v63
	v_exp_f32_e32 v220, v220
	v_mul_f32_e32 v222, 0xbfb8aa3b, v64
	v_exp_f32_e32 v222, v222
	v_fmamk_f32 v170, v170, 0x3b808081, v247
	v_mul_f32_e32 v224, 0xbfb8aa3b, v65
	v_rcp_f32_e32 v170, v170
	v_fmamk_f32 v220, v220, 0x3b808081, v247
	v_exp_f32_e32 v224, v224
	v_mul_f32_e32 v148, 0xbfb8aa3b, v58
	v_rcp_f32_e32 v220, v220
	v_exp_f32_e32 v219, v148
	v_mul_f32_e32 v221, 0xbfb8aa3b, v59
	v_fmamk_f32 v222, v222, 0x3b808081, v247
	v_exp_f32_e32 v221, v221
	v_rcp_f32_e32 v222, v222
	v_mul_f32_e32 v223, 0xbfb8aa3b, v60
	v_fmamk_f32 v224, v224, 0x3b808081, v247
	v_exp_f32_e32 v223, v223
	v_rcp_f32_e32 v224, v224
	v_fmamk_f32 v219, v219, 0x3b808081, v247
	v_mul_f32_e32 v225, 0xbfb8aa3b, v61
	v_cvt_pk_u8_f32 v170, v170, 0, 0
	v_rcp_f32_e32 v219, v219
	v_fmamk_f32 v221, v221, 0x3b808081, v247
	v_exp_f32_e32 v225, v225
	v_cvt_pk_u8_f32 v170, v220, 1, v170
	v_rcp_f32_e32 v221, v221
	v_fmamk_f32 v223, v223, 0x3b808081, v247
	v_cvt_pk_u8_f32 v170, v222, 2, v170
	v_rcp_f32_e32 v223, v223
	v_fmamk_f32 v225, v225, 0x3b808081, v247
	v_cvt_pk_u8_f32 v220, v224, 3, v170
	v_mov_b32_e32 v170, v219
	v_rcp_f32_e32 v225, v225
	v_cvt_pk_u8_f32 v170, v170, 0, 0
	v_cvt_pk_u8_f32 v170, v221, 1, v170
	s_mov_b64 s[0:1], 0x40000
	v_lshl_add_u64 v[148:149], v[146:147], 0, s[0:1]
	v_cvt_pk_u8_f32 v170, v223, 2, v170
	s_mov_b32 s0, 0x40000
	v_add_co_u32_e32 v222, vcc, s0, v146
	v_cvt_pk_u8_f32 v221, v225, 3, v170
	s_nop 0
	v_addc_co_u32_e32 v223, vcc, 0, v147, vcc
	v_mul_f32_e32 v170, 0xbfb8aa3b, v54
	v_exp_f32_e32 v170, v170
	global_store_dwordx2 v[222:223], v[220:221], off nt
	v_mul_f32_e32 v220, 0xbfb8aa3b, v55
	v_exp_f32_e32 v220, v220
	v_mul_f32_e32 v222, 0xbfb8aa3b, v56
	v_exp_f32_e32 v222, v222
	v_fmamk_f32 v170, v170, 0x3b808081, v247
	v_mul_f32_e32 v224, 0xbfb8aa3b, v57
	v_rcp_f32_e32 v170, v170
	v_fmamk_f32 v220, v220, 0x3b808081, v247
	v_exp_f32_e32 v224, v224
	v_mul_f32_e32 v219, 0xbfb8aa3b, v50
	v_rcp_f32_e32 v220, v220
	v_exp_f32_e32 v219, v219
	v_mul_f32_e32 v221, 0xbfb8aa3b, v51
	v_fmamk_f32 v222, v222, 0x3b808081, v247
	v_exp_f32_e32 v221, v221
	v_rcp_f32_e32 v222, v222
	v_mul_f32_e32 v223, 0xbfb8aa3b, v52
	v_fmamk_f32 v224, v224, 0x3b808081, v247
	v_exp_f32_e32 v223, v223
	v_rcp_f32_e32 v224, v224
	v_fmamk_f32 v219, v219, 0x3b808081, v247
	v_mul_f32_e32 v225, 0xbfb8aa3b, v53
	v_cvt_pk_u8_f32 v170, v170, 0, 0
	v_rcp_f32_e32 v219, v219
	v_fmamk_f32 v221, v221, 0x3b808081, v247
	v_exp_f32_e32 v225, v225
	v_cvt_pk_u8_f32 v170, v220, 1, v170
	v_rcp_f32_e32 v221, v221
	v_fmamk_f32 v223, v223, 0x3b808081, v247
	v_cvt_pk_u8_f32 v170, v222, 2, v170
	v_rcp_f32_e32 v223, v223
	v_fmamk_f32 v225, v225, 0x3b808081, v247
	v_cvt_pk_u8_f32 v220, v224, 3, v170
	v_mov_b32_e32 v170, v219
	v_rcp_f32_e32 v225, v225
	v_cvt_pk_u8_f32 v170, v170, 0, 0
	v_cvt_pk_u8_f32 v170, v221, 1, v170
	v_cvt_pk_u8_f32 v170, v223, 2, v170
	v_cvt_pk_u8_f32 v221, v225, 3, v170
	global_store_dwordx2 v[148:149], v[220:221], off offset:128 nt
	v_mul_f32_e32 v148, 0xbfb8aa3b, v46
	v_exp_f32_e32 v170, v148
	v_mul_f32_e32 v220, 0xbfb8aa3b, v47
	v_exp_f32_e32 v220, v220
	v_mul_f32_e32 v222, 0xbfb8aa3b, v48
	v_exp_f32_e32 v222, v222
	v_fmamk_f32 v170, v170, 0x3b808081, v247
	v_mul_f32_e32 v224, 0xbfb8aa3b, v49
	v_rcp_f32_e32 v170, v170
	v_fmamk_f32 v220, v220, 0x3b808081, v247
	v_exp_f32_e32 v224, v224
	v_mul_f32_e32 v148, 0xbfb8aa3b, v42
	v_rcp_f32_e32 v220, v220
	v_exp_f32_e32 v219, v148
	v_mul_f32_e32 v221, 0xbfb8aa3b, v43
	v_fmamk_f32 v222, v222, 0x3b808081, v247
	v_exp_f32_e32 v221, v221
	v_rcp_f32_e32 v222, v222
	v_mul_f32_e32 v223, 0xbfb8aa3b, v44
	v_fmamk_f32 v224, v224, 0x3b808081, v247
	v_exp_f32_e32 v223, v223
	v_rcp_f32_e32 v224, v224
	v_fmamk_f32 v219, v219, 0x3b808081, v247
	v_mul_f32_e32 v225, 0xbfb8aa3b, v45
	v_cvt_pk_u8_f32 v170, v170, 0, 0
	v_rcp_f32_e32 v219, v219
	v_fmamk_f32 v221, v221, 0x3b808081, v247
	v_exp_f32_e32 v225, v225
	v_cvt_pk_u8_f32 v170, v220, 1, v170
	v_rcp_f32_e32 v221, v221
	v_fmamk_f32 v223, v223, 0x3b808081, v247
	v_cvt_pk_u8_f32 v170, v222, 2, v170
	v_rcp_f32_e32 v223, v223
	v_fmamk_f32 v225, v225, 0x3b808081, v247
	v_cvt_pk_u8_f32 v220, v224, 3, v170
	v_mov_b32_e32 v170, v219
	v_rcp_f32_e32 v225, v225
	v_cvt_pk_u8_f32 v170, v170, 0, 0
	v_cvt_pk_u8_f32 v170, v221, 1, v170
	s_mov_b64 s[0:1], 0x48000
	v_lshl_add_u64 v[148:149], v[146:147], 0, s[0:1]
	v_cvt_pk_u8_f32 v170, v223, 2, v170
	s_mov_b32 s0, 0x48000
	v_add_co_u32_e32 v222, vcc, s0, v146
	v_cvt_pk_u8_f32 v221, v225, 3, v170
	s_nop 0
	v_addc_co_u32_e32 v223, vcc, 0, v147, vcc
	v_mul_f32_e32 v170, 0xbfb8aa3b, v38
	v_exp_f32_e32 v170, v170
	global_store_dwordx2 v[222:223], v[220:221], off nt
	v_mul_f32_e32 v220, 0xbfb8aa3b, v39
	v_exp_f32_e32 v220, v220
	v_mul_f32_e32 v222, 0xbfb8aa3b, v40
	v_exp_f32_e32 v222, v222
	v_fmamk_f32 v170, v170, 0x3b808081, v247
	v_mul_f32_e32 v224, 0xbfb8aa3b, v41
	v_rcp_f32_e32 v170, v170
	v_fmamk_f32 v220, v220, 0x3b808081, v247
	v_exp_f32_e32 v224, v224
	v_mul_f32_e32 v219, 0xbfb8aa3b, v34
	v_rcp_f32_e32 v220, v220
	v_exp_f32_e32 v219, v219
	v_mul_f32_e32 v221, 0xbfb8aa3b, v35
	v_fmamk_f32 v222, v222, 0x3b808081, v247
	v_exp_f32_e32 v221, v221
	v_rcp_f32_e32 v222, v222
	v_mul_f32_e32 v223, 0xbfb8aa3b, v36
	v_fmamk_f32 v224, v224, 0x3b808081, v247
	v_exp_f32_e32 v223, v223
	v_rcp_f32_e32 v224, v224
	v_fmamk_f32 v219, v219, 0x3b808081, v247
	v_mul_f32_e32 v225, 0xbfb8aa3b, v37
	v_cvt_pk_u8_f32 v170, v170, 0, 0
	v_rcp_f32_e32 v219, v219
	v_fmamk_f32 v221, v221, 0x3b808081, v247
	v_exp_f32_e32 v225, v225
	v_cvt_pk_u8_f32 v170, v220, 1, v170
	v_rcp_f32_e32 v221, v221
	v_fmamk_f32 v223, v223, 0x3b808081, v247
	v_cvt_pk_u8_f32 v170, v222, 2, v170
	v_rcp_f32_e32 v223, v223
	v_fmamk_f32 v225, v225, 0x3b808081, v247
	v_cvt_pk_u8_f32 v220, v224, 3, v170
	v_mov_b32_e32 v170, v219
	v_rcp_f32_e32 v225, v225
	v_cvt_pk_u8_f32 v170, v170, 0, 0
	v_cvt_pk_u8_f32 v170, v221, 1, v170
	v_cvt_pk_u8_f32 v170, v223, 2, v170
	v_cvt_pk_u8_f32 v221, v225, 3, v170
	global_store_dwordx2 v[148:149], v[220:221], off offset:128 nt
	v_mul_f32_e32 v148, 0xbfb8aa3b, v30
	v_exp_f32_e32 v170, v148
	v_mul_f32_e32 v220, 0xbfb8aa3b, v31
	v_exp_f32_e32 v220, v220
	v_mul_f32_e32 v222, 0xbfb8aa3b, v32
	v_exp_f32_e32 v222, v222
	v_fmamk_f32 v170, v170, 0x3b808081, v247
	v_mul_f32_e32 v224, 0xbfb8aa3b, v33
	v_rcp_f32_e32 v170, v170
	v_fmamk_f32 v220, v220, 0x3b808081, v247
	v_exp_f32_e32 v224, v224
	v_mul_f32_e32 v148, 0xbfb8aa3b, v26
	v_rcp_f32_e32 v220, v220
	v_exp_f32_e32 v219, v148
	v_mul_f32_e32 v221, 0xbfb8aa3b, v27
	v_fmamk_f32 v222, v222, 0x3b808081, v247
	v_exp_f32_e32 v221, v221
	v_rcp_f32_e32 v222, v222
	v_mul_f32_e32 v223, 0xbfb8aa3b, v28
	v_fmamk_f32 v224, v224, 0x3b808081, v247
	v_exp_f32_e32 v223, v223
	v_rcp_f32_e32 v224, v224
	v_fmamk_f32 v219, v219, 0x3b808081, v247
	v_mul_f32_e32 v225, 0xbfb8aa3b, v29
	v_cvt_pk_u8_f32 v170, v170, 0, 0
	v_rcp_f32_e32 v219, v219
	v_fmamk_f32 v221, v221, 0x3b808081, v247
	v_exp_f32_e32 v225, v225
	v_cvt_pk_u8_f32 v170, v220, 1, v170
	v_rcp_f32_e32 v221, v221
	v_fmamk_f32 v223, v223, 0x3b808081, v247
	v_cvt_pk_u8_f32 v170, v222, 2, v170
	v_rcp_f32_e32 v223, v223
	v_fmamk_f32 v225, v225, 0x3b808081, v247
	v_cvt_pk_u8_f32 v220, v224, 3, v170
	v_mov_b32_e32 v170, v219
	v_rcp_f32_e32 v225, v225
	v_cvt_pk_u8_f32 v170, v170, 0, 0
	v_cvt_pk_u8_f32 v170, v221, 1, v170
	s_mov_b64 s[0:1], 0x50000
	v_lshl_add_u64 v[148:149], v[146:147], 0, s[0:1]
	v_cvt_pk_u8_f32 v170, v223, 2, v170
	s_mov_b32 s0, 0x50000
	v_add_co_u32_e32 v222, vcc, s0, v146
	v_cvt_pk_u8_f32 v221, v225, 3, v170
	s_nop 0
	v_addc_co_u32_e32 v223, vcc, 0, v147, vcc
	v_mul_f32_e32 v170, 0xbfb8aa3b, v22
	v_exp_f32_e32 v170, v170
	global_store_dwordx2 v[222:223], v[220:221], off nt
	v_mul_f32_e32 v220, 0xbfb8aa3b, v23
	v_exp_f32_e32 v220, v220
	v_mul_f32_e32 v222, 0xbfb8aa3b, v24
	v_exp_f32_e32 v222, v222
	v_fmamk_f32 v170, v170, 0x3b808081, v247
	v_mul_f32_e32 v224, 0xbfb8aa3b, v25
	v_rcp_f32_e32 v170, v170
	v_fmamk_f32 v220, v220, 0x3b808081, v247
	v_exp_f32_e32 v224, v224
	v_mul_f32_e32 v219, 0xbfb8aa3b, v18
	v_rcp_f32_e32 v220, v220
	v_exp_f32_e32 v219, v219
	v_mul_f32_e32 v221, 0xbfb8aa3b, v19
	v_fmamk_f32 v222, v222, 0x3b808081, v247
	v_exp_f32_e32 v221, v221
	v_rcp_f32_e32 v222, v222
	v_mul_f32_e32 v223, 0xbfb8aa3b, v20
	v_fmamk_f32 v224, v224, 0x3b808081, v247
	v_exp_f32_e32 v223, v223
	v_rcp_f32_e32 v224, v224
	v_fmamk_f32 v219, v219, 0x3b808081, v247
	v_mul_f32_e32 v225, 0xbfb8aa3b, v21
	v_cvt_pk_u8_f32 v170, v170, 0, 0
	v_rcp_f32_e32 v219, v219
	v_fmamk_f32 v221, v221, 0x3b808081, v247
	v_exp_f32_e32 v225, v225
	v_cvt_pk_u8_f32 v170, v220, 1, v170
	v_rcp_f32_e32 v221, v221
	v_fmamk_f32 v223, v223, 0x3b808081, v247
	v_cvt_pk_u8_f32 v170, v222, 2, v170
	v_rcp_f32_e32 v223, v223
	v_fmamk_f32 v225, v225, 0x3b808081, v247
	v_cvt_pk_u8_f32 v220, v224, 3, v170
	v_mov_b32_e32 v170, v219
	v_rcp_f32_e32 v225, v225
	v_cvt_pk_u8_f32 v170, v170, 0, 0
	v_cvt_pk_u8_f32 v170, v221, 1, v170
	v_cvt_pk_u8_f32 v170, v223, 2, v170
	v_cvt_pk_u8_f32 v221, v225, 3, v170
	global_store_dwordx2 v[148:149], v[220:221], off offset:128 nt
	v_mul_f32_e32 v148, 0xbfb8aa3b, v14
	v_exp_f32_e32 v170, v148
	v_mul_f32_e32 v220, 0xbfb8aa3b, v15
	v_exp_f32_e32 v220, v220
	v_mul_f32_e32 v222, 0xbfb8aa3b, v16
	v_exp_f32_e32 v222, v222
	v_fmamk_f32 v170, v170, 0x3b808081, v247
	v_mul_f32_e32 v224, 0xbfb8aa3b, v17
	v_rcp_f32_e32 v170, v170
	v_fmamk_f32 v220, v220, 0x3b808081, v247
	v_exp_f32_e32 v224, v224
	v_mul_f32_e32 v148, 0xbfb8aa3b, v10
	v_rcp_f32_e32 v220, v220
	v_exp_f32_e32 v219, v148
	v_mul_f32_e32 v221, 0xbfb8aa3b, v11
	v_fmamk_f32 v222, v222, 0x3b808081, v247
	v_exp_f32_e32 v221, v221
	v_rcp_f32_e32 v222, v222
	v_mul_f32_e32 v223, 0xbfb8aa3b, v12
	v_fmamk_f32 v224, v224, 0x3b808081, v247
	v_exp_f32_e32 v223, v223
	v_rcp_f32_e32 v224, v224
	v_fmamk_f32 v219, v219, 0x3b808081, v247
	v_mul_f32_e32 v225, 0xbfb8aa3b, v13
	v_cvt_pk_u8_f32 v170, v170, 0, 0
	v_rcp_f32_e32 v219, v219
	v_fmamk_f32 v221, v221, 0x3b808081, v247
	v_exp_f32_e32 v225, v225
	v_cvt_pk_u8_f32 v170, v220, 1, v170
	v_rcp_f32_e32 v221, v221
	v_fmamk_f32 v223, v223, 0x3b808081, v247
	v_cvt_pk_u8_f32 v170, v222, 2, v170
	v_rcp_f32_e32 v223, v223
	v_fmamk_f32 v225, v225, 0x3b808081, v247
	v_cvt_pk_u8_f32 v220, v224, 3, v170
	v_mov_b32_e32 v170, v219
	v_rcp_f32_e32 v225, v225
	v_cvt_pk_u8_f32 v170, v170, 0, 0
	v_cvt_pk_u8_f32 v170, v221, 1, v170
	v_cvt_pk_u8_f32 v170, v223, 2, v170
	v_cvt_pk_u8_f32 v221, v225, 3, v170
	v_mul_f32_e32 v170, 0xbfb8aa3b, v6
	s_mov_b64 s[0:1], 0x58000
	v_exp_f32_e32 v170, v170
	v_lshl_add_u64 v[148:149], v[146:147], 0, s[0:1]
	s_mov_b32 s0, 0x58000
	v_add_co_u32_e32 v146, vcc, s0, v146
	v_mul_f32_e32 v219, 0xbfb8aa3b, v2
	s_nop 0
	v_addc_co_u32_e32 v147, vcc, 0, v147, vcc
	global_store_dwordx2 v[146:147], v[220:221], off nt
	v_fmamk_f32 v146, v170, 0x3b808081, v247
	v_mul_f32_e32 v170, 0xbfb8aa3b, v7
	v_exp_f32_e32 v170, v170
	v_exp_f32_e32 v219, v219
	v_mul_f32_e32 v220, 0xbfb8aa3b, v8
	v_exp_f32_e32 v220, v220
	v_mul_f32_e32 v222, 0xbfb8aa3b, v9
	v_rcp_f32_e32 v146, v146
	v_fmamk_f32 v170, v170, 0x3b808081, v247
	v_exp_f32_e32 v222, v222
	v_fmamk_f32 v147, v219, 0x3b808081, v247
	v_mul_f32_e32 v219, 0xbfb8aa3b, v3
	v_rcp_f32_e32 v170, v170
	v_exp_f32_e32 v219, v219
	v_fmamk_f32 v220, v220, 0x3b808081, v247
	v_mul_f32_e32 v221, 0xbfb8aa3b, v4
	v_rcp_f32_e32 v220, v220
	v_exp_f32_e32 v221, v221
	v_fmamk_f32 v222, v222, 0x3b808081, v247
	v_mul_f32_e32 v223, 0xbfb8aa3b, v5
	v_rcp_f32_e32 v222, v222
	v_rcp_f32_e32 v147, v147
	v_fmamk_f32 v219, v219, 0x3b808081, v247
	v_exp_f32_e32 v223, v223
	v_cvt_pk_u8_f32 v146, v146, 0, 0
	v_rcp_f32_e32 v219, v219
	v_cvt_pk_u8_f32 v146, v170, 1, v146
	v_fmamk_f32 v221, v221, 0x3b808081, v247
	v_rcp_f32_e32 v221, v221
	v_cvt_pk_u8_f32 v146, v220, 2, v146
	v_fmamk_f32 v223, v223, 0x3b808081, v247
	v_rcp_f32_e32 v223, v223
	v_cvt_pk_u8_f32 v146, v222, 3, v146
	v_cvt_pk_u8_f32 v147, v147, 0, 0
	v_cvt_pk_u8_f32 v147, v219, 1, v147
	v_cvt_pk_u8_f32 v147, v221, 2, v147
	v_cvt_pk_u8_f32 v147, v223, 3, v147
	global_store_dwordx2 v[148:149], v[146:147], off offset:128 nt
	s_mov_b64 s[2:3], 0

.LBB0_834:
	s_waitcnt vmcnt(0)
	s_barrier
	s_and_saveexec_b64 s[6:7], s[80:81]
	s_cbranch_execz .LBB0_849
	s_add_i32 s0, 0, 0x20164
	v_mov_b32_e32 v2, s0
	v_readlane_b32 s0, v246, 2
	v_mov_b32_e32 v3, 0x3000
	v_readlane_b32 s1, v246, 3
	ds_read_b32 v2, v2
	s_add_u32 s10, s0, 0x3200
	s_addc_u32 s11, s1, 0
	s_nop 1
	v_mov_b32_e32 v248, 0x3000
	global_load_dword v247, v248, s[0:1] offset:832 sc1
	global_load_dword v3, v3, s[0:1] offset:512 sc1
	buffer_inv sc1
	s_waitcnt vmcnt(0) lgkmcnt(0)
	v_cmp_ge_u32_e64 s[98:99], v247, v2
	v_cmp_ge_u32_e32 vcc, v3, v2
	s_cmp_lg_u32 s98, 0
	s_cselect_b32 s100, 1, 0
	s_cbranch_vccnz .LBB0_849
	v_readlane_b32 s0, v246, 2
	v_readlane_b32 s1, v246, 3
	s_add_u32 s8, s0, 0x4200
	s_addc_u32 s9, s1, 0
	s_mov_b32 s0, 1
	v_mov_b32_e32 v3, 0
	s_branch .LBB0_838

.LBB0_849:
	s_or_b64 exec, exec, s[6:7]
	s_waitcnt lgkmcnt(0)
	s_barrier
	s_and_saveexec_b64 s[6:7], s[80:81]
	s_cbranch_execz .LBB0_864
	s_cmp_eq_u32 s100, 1
	s_cbranch_scc1 .LBB0_864
	s_add_i32 s0, 0, 0x20164
	v_mov_b32_e32 v2, s0
	v_readlane_b32 s0, v246, 2
	v_mov_b32_e32 v3, 0x3000
	v_readlane_b32 s1, v246, 3
	ds_read_b32 v2, v2
	s_add_u32 s10, s0, 0x3340
	s_addc_u32 s11, s1, 0
	s_nop 1
	global_load_dword v3, v3, s[0:1] offset:832 sc1
	buffer_inv sc1
	s_waitcnt vmcnt(0) lgkmcnt(0)
	v_cmp_ge_u32_e32 vcc, v3, v2
	s_cbranch_vccnz .LBB0_864
	v_readlane_b32 s0, v246, 2
	v_readlane_b32 s1, v246, 3
	s_add_u32 s8, s0, 0x4200
	s_addc_u32 s9, s1, 0
	s_mov_b32 s0, 1
	v_mov_b32_e32 v3, 0
	s_branch .LBB0_853
